# pool window-sum loops unrolled x2 with the next row read in flight
# speedup vs baseline: 1.0225x; 1.0077x over previous
; DI unsigned pk2(float lo, float hi) { f32x2 v = {lo, hi}; bfv2 b = __builtin_convertvector(v, bfv2); return __builtin_bit_cast(unsigned, b); }
; DI f32x16 mfma32(bf16x8 a, bf16x8 b, f32x16 c) { return __builtin_amdgcn_mfma_f32_32x32x16_bf16(a, b, c, 0, 0, 0); }
; DI void unpack8(u32x4 v, float* x) { x[0] = bflo(v.x); x[1] = bfhi(v.x); x[2] = bflo(v.y); x[3] = bfhi(v.y); x[4] = bflo(v.z); x[5] = bfhi(v.z); x[6] = bflo(v.w); x[7] = bfhi(v.w); }
; DI void pool_task(const Params& p, int layer, int tile, unsigned char* lds) {
;     ...
;     if (t >= s0 && t < s0 + S) v = *(const u32x4*)(proj + (size_t)t * PP + D_X + 64 * g + dc);
;     *(u32x4*)(xs + rr * 72 + dc) = v;
;   }
;   __syncthreads();
;   f32x16 acc[2][2];
; #pragma unroll
;   for (int a = 0; a < 2; ++a)
; #pragma unroll
;     for (int b = 0; b < 2; ++b)
; #pragma unroll
;       for (int i = 0; i < 16; ++i) acc[a][b][i] = 0.f;
;   const bf16_t* WT = (const bf16_t*)(p.ws + WS_POOLW) + (size_t)(layer * 4 + g) * 4096;
; #pragma unroll
;   for (int mt = 0; mt < 2; ++mt) {
;     const int tl = 32 * mt + r, pos = t0 + tl - s0;
;     const int lo = max(pos - half, 0), hi = min(pos + half, S);
;     const float inv = 1.f / (float)(hi - lo);
; #pragma unroll
;     for (int ks = 0; ks < 4; ++ks) {
;       float sum[8];
; #pragma unroll
;       for (int e = 0; e < 8; ++e) sum[e] = 0.f;
;       for (int w = 0; w < 2 * half; ++w) {
;         float x[8]; unpack8(*(const u32x4*)(xs + (tl + 8 - half + w) * 72 + 16 * ks + 8 * hh), x);
; #pragma unroll
;         for (int e = 0; e < 8; ++e) sum[e] += x[e];
;       }
;       float x0[8]; unpack8(*(const u32x4*)(xs + (tl + 8) * 72 + 16 * ks + 8 * hh), x0);
;       const u32x4 w4 = {pk2(sum[0] * inv - x0[0], sum[1] * inv - x0[1]), pk2(sum[2] * inv - x0[2], sum[3] * inv - x0[3]), pk2(sum[4] * inv - x0[4], sum[5] * inv - x0[5]), pk2(sum[6] * inv - x0[6], sum[7] * inv - x0[7])};
;       const bf16x8 a = __builtin_bit_cast(bf16x8, w4);
; #pragma unroll
;       for (int nt = 0; nt < 2; ++nt) { const bf16x8 b = *(const bf16x8*)(WT + (32 * nt + r) * 64 + 16 * ks + 8 * hh); acc[mt][nt] = mfma32(a, b, acc[mt][nt]); }
;     }
.Lpoolin_9:
	s_or_b64 exec, exec, s[8:9]
	s_waitcnt vmcnt(0)
	ds_write_b128 v10, v[116:119]
	ds_write_b128 v10, v[120:123] offset:1152
	ds_write_b128 v10, v[124:127] offset:2304
	ds_write_b128 v10, v[128:131] offset:3456
	ds_write_b128 v10, v[132:135] offset:4608
	ds_write_b128 v10, v[136:139] offset:5760
	ds_write_b128 v10, v[140:143] offset:6912
	ds_write_b128 v10, v[144:147] offset:8064
	ds_write_b128 v10, v[148:151] offset:9216
	ds_write_b128 v10, v[152:155] offset:10368
	v_and_b32_e32 v101, 63, v100
	v_lshrrev_b32_e32 v103, 5, v101
	v_and_b32_e32 v104, 31, v100
	v_lshlrev_b32_e64 v55, v102, 1
	v_lshlrev_b32_e64 v105, v102, 2
	v_lshlrev_b32_e32 v160, 4, v103
	v_mov_b32_e32 v3, 0
	v_mul_u32_u24_e32 v9, 0x90, v104
	v_cmp_lt_i32_e64 s[38:39], 0, v105
	v_mul_lo_u32 v106, v55, s94
	v_add3_u32 v107, v8, v9, v160
	v_mov_b32_e32 v2, v3
	v_mov_b32_e32 v5, v3
	v_mov_b32_e32 v4, v3
	v_mov_b32_e32 v7, v3
	v_mov_b32_e32 v6, v3
	v_mov_b32_e32 v1, v3
	v_mov_b32_e32 v0, v3
	s_waitcnt lgkmcnt(0)
	s_barrier
	s_and_saveexec_b64 s[0:1], s[38:39]
	s_cbranch_execz .LBB0_143
	v_sub_u32_e32 v0, v107, v106
	v_readlane_b32 s2, v246, 33
	s_mov_b64 s[8:9], 0
	v_mov_b32_e32 v10, v105
	v_add_u32_e32 v8, s2, v0
	v_mov_b32_e32 v0, 0
	v_mov_b32_e32 v1, v0
	v_mov_b32_e32 v6, v0
	v_mov_b32_e32 v7, v0
	v_mov_b32_e32 v4, v0
	v_mov_b32_e32 v5, v0
	v_mov_b32_e32 v2, v0
	v_mov_b32_e32 v3, v0
	ds_read_b128 v[12:15], v8
	v_add_u32_e32 v8, 0x90, v8
.LBB0_141:
	ds_read_b128 v[236:239], v8
	v_add_u32_e32 v10, -2, v10
	v_cmp_eq_u32_e32 vcc, 0, v10
	v_add_u32_e32 v8, 0x90, v8
	s_or_b64 s[8:9], vcc, s[8:9]
	s_waitcnt lgkmcnt(1)
	v_lshlrev_b32_e32 v16, 16, v12
	v_and_b32_e32 v17, 0xffff0000, v12
	v_lshlrev_b32_e32 v12, 16, v13
	v_and_b32_e32 v13, 0xffff0000, v13
	v_pk_add_f32 v[4:5], v[4:5], v[12:13]
	v_lshlrev_b32_e32 v12, 16, v14
	v_and_b32_e32 v13, 0xffff0000, v14
	v_pk_add_f32 v[2:3], v[2:3], v[12:13]
	v_lshlrev_b32_e32 v12, 16, v15
	v_and_b32_e32 v13, 0xffff0000, v15
	v_pk_add_f32 v[6:7], v[6:7], v[16:17]
	v_pk_add_f32 v[0:1], v[0:1], v[12:13]
	ds_read_b128 v[12:15], v8
	v_add_u32_e32 v8, 0x90, v8
	s_waitcnt lgkmcnt(1)
	v_lshlrev_b32_e32 v16, 16, v236
	v_and_b32_e32 v17, 0xffff0000, v236
	v_lshlrev_b32_e32 v236, 16, v237
	v_and_b32_e32 v237, 0xffff0000, v237
	v_pk_add_f32 v[4:5], v[4:5], v[236:237]
	v_lshlrev_b32_e32 v236, 16, v238
	v_and_b32_e32 v237, 0xffff0000, v238
	v_pk_add_f32 v[2:3], v[2:3], v[236:237]
	v_lshlrev_b32_e32 v236, 16, v239
	v_and_b32_e32 v237, 0xffff0000, v239
	v_pk_add_f32 v[6:7], v[6:7], v[16:17]
	v_pk_add_f32 v[0:1], v[0:1], v[236:237]
	s_andn2_b64 exec, exec, s[8:9]
	s_cbranch_execnz .LBB0_141
	s_or_b64 exec, exec, s[8:9]
	s_waitcnt lgkmcnt(0)
.LBB0_143:
	s_or_b64 exec, exec, s[0:1]
	v_or_b32_e32 v8, s34, v104
	v_subrev_u32_e32 v12, s35, v8
	v_sub_u32_e32 v13, v12, v55
	v_add_u32_e32 v12, v12, v55
	v_max_i32_e32 v13, 0, v13
	v_min_i32_e32 v12, s21, v12
	v_sub_u32_e32 v12, v12, v13
	v_cvt_f32_i32_e32 v16, v12
	v_add_u32_e32 v10, s29, v102
	v_ashrrev_i32_e32 v11, 31, v10
	v_readlane_b32 s0, v247, 22
	v_lshlrev_b64 v[10:11], 13, v[10:11]
	v_readlane_b32 s1, v247, 23
	v_add3_u32 v57, v54, v9, v160
	v_div_scale_f32 v19, vcc, 1.0, v16, 1.0
	v_lshl_add_u64 v[10:11], s[0:1], 0, v[10:11]
	v_div_scale_f32 v17, s[0:1], v16, v16, 1.0
	v_rcp_f32_e32 v18, v17
	v_lshl_add_u64 v[40:41], v[10:11], 0, v[160:161]
	v_lshlrev_b32_e32 v10, 7, v104
	v_mov_b32_e32 v11, v161
	v_fma_f32 v20, -v17, v18, 1.0
	v_fmac_f32_e32 v18, v20, v18
	v_lshl_add_u64 v[42:43], v[40:41], 0, v[10:11]
	ds_read_b128 v[8:11], v57 offset:1152
	v_mul_f32_e32 v20, v19, v18
	v_fma_f32 v21, -v17, v20, v19
	v_fmac_f32_e32 v20, v21, v18
	v_fma_f32 v17, -v17, v20, v19
	v_div_fmas_f32 v17, v17, v18, v20
	s_waitcnt lgkmcnt(0)
	v_lshlrev_b32_e32 v12, 16, v8
	v_and_b32_e32 v13, 0xffff0000, v8
	v_lshlrev_b32_e32 v8, 16, v9
	v_and_b32_e32 v9, 0xffff0000, v9
	v_div_fixup_f32 v44, v17, v16, 1.0
	v_lshlrev_b32_e32 v14, 16, v10
	v_and_b32_e32 v15, 0xffff0000, v10
	v_lshlrev_b32_e32 v10, 16, v11
	v_and_b32_e32 v11, 0xffff0000, v11
	v_pk_fma_f32 v[4:5], v[44:45], v[4:5], v[8:9] op_sel_hi:[0,1,1] neg_lo:[0,0,1] neg_hi:[0,0,1]
	v_pk_fma_f32 v[8:9], v[44:45], v[0:1], v[10:11] op_sel_hi:[0,1,1] neg_lo:[0,0,1] neg_hi:[0,0,1]
	v_cvt_pk_bf16_f32 v1, v4, v5
	v_lshl_or_b32 v4, v104, 6, v192
	v_lshlrev_b32_e32 v160, 1, v4
	v_lshl_add_u64 v[4:5], v[40:41], 0, v[160:161]
	global_load_dwordx4 v[32:35], v[42:43], off
	global_load_dwordx4 v[36:39], v[4:5], off
	v_pk_fma_f32 v[6:7], v[44:45], v[6:7], v[12:13] op_sel_hi:[0,1,1] neg_lo:[0,0,1] neg_hi:[0,0,1]
	v_pk_fma_f32 v[2:3], v[44:45], v[2:3], v[14:15] op_sel_hi:[0,1,1] neg_lo:[0,0,1] neg_hi:[0,0,1]
	v_cvt_pk_bf16_f32 v0, v6, v7
	v_cvt_pk_bf16_f32 v2, v2, v3
	v_cvt_pk_bf16_f32 v3, v8, v9
	v_mov_b32_e32 v49, 0
	v_mov_b32_e32 v48, v49
	v_mov_b32_e32 v51, v49
	v_mov_b32_e32 v50, v49
	v_mov_b32_e32 v53, v49
	v_mov_b32_e32 v52, v49
	v_mov_b32_e32 v47, v49
	v_mov_b32_e32 v46, v49
	s_waitcnt vmcnt(1)
	v_mfma_f32_32x32x16_bf16 v[16:31], v[0:3], v[32:35], 0
	s_waitcnt vmcnt(0)
	v_mfma_f32_32x32x16_bf16 v[0:15], v[0:3], v[36:39], 0
	s_and_saveexec_b64 s[0:1], s[38:39]
	s_cbranch_execz .LBB0_147
	v_sub_u32_e32 v45, v107, v106
	v_readlane_b32 s2, v246, 34
	v_mov_b32_e32 v46, 0
	s_mov_b64 s[8:9], 0
	v_add_u32_e32 v45, s2, v45
	v_mov_b32_e32 v56, v105
	v_mov_b32_e32 v47, v46
	v_mov_b32_e32 v52, v46
	v_mov_b32_e32 v53, v46
	v_mov_b32_e32 v50, v46
	v_mov_b32_e32 v51, v46
	v_mov_b32_e32 v48, v46
	v_mov_b32_e32 v49, v46
	ds_read_b128 v[58:61], v45
	v_add_u32_e32 v45, 0x90, v45
; DI unsigned pk2(float lo, float hi) { f32x2 v = {lo, hi}; bfv2 b = __builtin_convertvector(v, bfv2); return __builtin_bit_cast(unsigned, b); }
; DI f32x16 mfma32(bf16x8 a, bf16x8 b, f32x16 c) { return __builtin_amdgcn_mfma_f32_32x32x16_bf16(a, b, c, 0, 0, 0); }
; DI void unpack8(u32x4 v, float* x) { x[0] = bflo(v.x); x[1] = bfhi(v.x); x[2] = bflo(v.y); x[3] = bfhi(v.y); x[4] = bflo(v.z); x[5] = bfhi(v.z); x[6] = bflo(v.w); x[7] = bfhi(v.w); }
; DI void pool_task(const Params& p, int layer, int tile, unsigned char* lds) {
;     ...
;     for (int ks = 0; ks < 4; ++ks) {
;       float sum[8];
; #pragma unroll
;       for (int e = 0; e < 8; ++e) sum[e] = 0.f;
;       for (int w = 0; w < 2 * half; ++w) {
;         float x[8]; unpack8(*(const u32x4*)(xs + (tl + 8 - half + w) * 72 + 16 * ks + 8 * hh), x);
; #pragma unroll
;         for (int e = 0; e < 8; ++e) sum[e] += x[e];
;       }
;       float x0[8]; unpack8(*(const u32x4*)(xs + (tl + 8) * 72 + 16 * ks + 8 * hh), x0);
;       const u32x4 w4 = {pk2(sum[0] * inv - x0[0], sum[1] * inv - x0[1]), pk2(sum[2] * inv - x0[2], sum[3] * inv - x0[3]), pk2(sum[4] * inv - x0[4], sum[5] * inv - x0[5]), pk2(sum[6] * inv - x0[6], sum[7] * inv - x0[7])};
;       const bf16x8 a = __builtin_bit_cast(bf16x8, w4);
; #pragma unroll
;       for (int nt = 0; nt < 2; ++nt) { const bf16x8 b = *(const bf16x8*)(WT + (32 * nt + r) * 64 + 16 * ks + 8 * hh); acc[mt][nt] = mfma32(a, b, acc[mt][nt]); }
;     }
.LBB0_145:
	ds_read_b128 v[236:239], v45
	v_add_u32_e32 v56, -2, v56
	v_cmp_eq_u32_e32 vcc, 0, v56
	v_add_u32_e32 v45, 0x90, v45
	s_or_b64 s[8:9], vcc, s[8:9]
	s_waitcnt lgkmcnt(1)
	v_lshlrev_b32_e32 v62, 16, v58
	v_and_b32_e32 v63, 0xffff0000, v58
	v_lshlrev_b32_e32 v58, 16, v59
	v_and_b32_e32 v59, 0xffff0000, v59
	v_pk_add_f32 v[50:51], v[50:51], v[58:59]
	v_lshlrev_b32_e32 v58, 16, v60
	v_and_b32_e32 v59, 0xffff0000, v60
	v_pk_add_f32 v[48:49], v[48:49], v[58:59]
	v_lshlrev_b32_e32 v58, 16, v61
	v_and_b32_e32 v59, 0xffff0000, v61
	v_pk_add_f32 v[52:53], v[52:53], v[62:63]
	v_pk_add_f32 v[46:47], v[46:47], v[58:59]
	ds_read_b128 v[58:61], v45
	v_add_u32_e32 v45, 0x90, v45
	s_waitcnt lgkmcnt(1)
	v_lshlrev_b32_e32 v62, 16, v236
	v_and_b32_e32 v63, 0xffff0000, v236
	v_lshlrev_b32_e32 v236, 16, v237
	v_and_b32_e32 v237, 0xffff0000, v237
	v_pk_add_f32 v[50:51], v[50:51], v[236:237]
	v_lshlrev_b32_e32 v236, 16, v238
	v_and_b32_e32 v237, 0xffff0000, v238
	v_pk_add_f32 v[48:49], v[48:49], v[236:237]
	v_lshlrev_b32_e32 v236, 16, v239
	v_and_b32_e32 v237, 0xffff0000, v239
	v_pk_add_f32 v[52:53], v[52:53], v[62:63]
	v_pk_add_f32 v[46:47], v[46:47], v[236:237]
	s_andn2_b64 exec, exec, s[8:9]
	s_cbranch_execnz .LBB0_145
	s_or_b64 exec, exec, s[8:9]
	s_waitcnt lgkmcnt(0)
.LBB0_147:
	s_or_b64 exec, exec, s[0:1]
	ds_read_b128 v[58:61], v57 offset:1184
	v_mov_b32_e32 v45, v44
	global_load_dwordx4 v[64:67], v[42:43], off offset:32
	v_lshlrev_b32_e32 v56, 3, v103
	s_waitcnt lgkmcnt(0)
	v_lshlrev_b32_e32 v62, 16, v58
	v_and_b32_e32 v63, 0xffff0000, v58
	v_pk_fma_f32 v[52:53], v[44:45], v[52:53], v[62:63] neg_lo:[0,0,1] neg_hi:[0,0,1]
	s_nop 0
	v_cvt_pk_bf16_f32 v58, v52, v53
	v_lshlrev_b32_e32 v52, 16, v59
	v_and_b32_e32 v53, 0xffff0000, v59
	v_pk_fma_f32 v[50:51], v[44:45], v[50:51], v[52:53] neg_lo:[0,0,1] neg_hi:[0,0,1]
	s_nop 0
	v_cvt_pk_bf16_f32 v59, v50, v51
	v_lshlrev_b32_e32 v50, 16, v60
	v_and_b32_e32 v51, 0xffff0000, v60
	v_pk_fma_f32 v[48:49], v[44:45], v[48:49], v[50:51] neg_lo:[0,0,1] neg_hi:[0,0,1]
	s_nop 0
	v_cvt_pk_bf16_f32 v60, v48, v49
	v_lshlrev_b32_e32 v48, 16, v61
	v_and_b32_e32 v49, 0xffff0000, v61
	v_pk_fma_f32 v[46:47], v[44:45], v[46:47], v[48:49] neg_lo:[0,0,1] neg_hi:[0,0,1]
	v_mov_b32_e32 v49, 0
	v_cvt_pk_bf16_f32 v61, v46, v47
	v_lshl_add_u64 v[46:47], v[40:41], 0, v[160:161]
	global_load_dwordx4 v[68:71], v[46:47], off offset:32
	v_mov_b32_e32 v48, v49
	v_mov_b32_e32 v51, v49
	v_mov_b32_e32 v50, v49
	v_mov_b32_e32 v53, v49
	v_mov_b32_e32 v52, v49
	v_mov_b32_e32 v47, v49
	v_mov_b32_e32 v46, v49
	s_waitcnt vmcnt(1)
	v_mfma_f32_32x32x16_bf16 v[16:31], v[58:61], v[64:67], v[16:31]
	s_waitcnt vmcnt(0)
	v_mfma_f32_32x32x16_bf16 v[0:15], v[58:61], v[68:71], v[0:15]
	s_and_saveexec_b64 s[0:1], s[38:39]
	s_cbranch_execz .LBB0_151
	v_sub_u32_e32 v46, v107, v106
	v_readlane_b32 s2, v246, 35
	s_mov_b64 s[8:9], 0
	v_mov_b32_e32 v59, v105
	v_add_u32_e32 v58, s2, v46
	v_mov_b32_e32 v46, 0
	v_mov_b32_e32 v47, v46
	v_mov_b32_e32 v52, v46
	v_mov_b32_e32 v53, v46
	v_mov_b32_e32 v50, v46
	v_mov_b32_e32 v51, v46
	v_mov_b32_e32 v48, v46
	v_mov_b32_e32 v49, v46
	ds_read_b128 v[60:63], v58
	v_add_u32_e32 v58, 0x90, v58
.LBB0_149:
	ds_read_b128 v[236:239], v58
	v_add_u32_e32 v59, -2, v59
	v_cmp_eq_u32_e32 vcc, 0, v59
	v_add_u32_e32 v58, 0x90, v58
	s_or_b64 s[8:9], vcc, s[8:9]
	s_waitcnt lgkmcnt(1)
	v_lshlrev_b32_e32 v72, 16, v60
	v_and_b32_e32 v73, 0xffff0000, v60
	v_lshlrev_b32_e32 v60, 16, v61
	v_and_b32_e32 v61, 0xffff0000, v61
	v_pk_add_f32 v[50:51], v[50:51], v[60:61]
	v_lshlrev_b32_e32 v60, 16, v62
	v_and_b32_e32 v61, 0xffff0000, v62
	v_pk_add_f32 v[48:49], v[48:49], v[60:61]
	v_lshlrev_b32_e32 v60, 16, v63
	v_and_b32_e32 v61, 0xffff0000, v63
	v_pk_add_f32 v[52:53], v[52:53], v[72:73]
	v_pk_add_f32 v[46:47], v[46:47], v[60:61]
	ds_read_b128 v[60:63], v58
	v_add_u32_e32 v58, 0x90, v58
	s_waitcnt lgkmcnt(1)
	v_lshlrev_b32_e32 v72, 16, v236
	v_and_b32_e32 v73, 0xffff0000, v236
	v_lshlrev_b32_e32 v236, 16, v237
	v_and_b32_e32 v237, 0xffff0000, v237
	v_pk_add_f32 v[50:51], v[50:51], v[236:237]
	v_lshlrev_b32_e32 v236, 16, v238
	v_and_b32_e32 v237, 0xffff0000, v238
	v_pk_add_f32 v[48:49], v[48:49], v[236:237]
	v_lshlrev_b32_e32 v236, 16, v239
	v_and_b32_e32 v237, 0xffff0000, v239
	v_pk_add_f32 v[52:53], v[52:53], v[72:73]
	v_pk_add_f32 v[46:47], v[46:47], v[236:237]
	s_andn2_b64 exec, exec, s[8:9]
	s_cbranch_execnz .LBB0_149
	s_or_b64 exec, exec, s[8:9]
	s_waitcnt lgkmcnt(0)
.LBB0_151:
	s_or_b64 exec, exec, s[0:1]
	ds_read_b128 v[58:61], v57 offset:1216
	global_load_dwordx4 v[72:75], v[42:43], off offset:64
	s_waitcnt lgkmcnt(0)
	v_lshlrev_b32_e32 v62, 16, v58
	v_and_b32_e32 v63, 0xffff0000, v58
	v_pk_fma_f32 v[52:53], v[44:45], v[52:53], v[62:63] neg_lo:[0,0,1] neg_hi:[0,0,1]
	s_nop 0
	v_cvt_pk_bf16_f32 v58, v52, v53
	v_lshlrev_b32_e32 v52, 16, v59
	v_and_b32_e32 v53, 0xffff0000, v59
	v_pk_fma_f32 v[50:51], v[44:45], v[50:51], v[52:53] neg_lo:[0,0,1] neg_hi:[0,0,1]
	s_nop 0
	v_cvt_pk_bf16_f32 v59, v50, v51
	v_lshlrev_b32_e32 v50, 16, v60
	v_and_b32_e32 v51, 0xffff0000, v60
	v_pk_fma_f32 v[48:49], v[44:45], v[48:49], v[50:51] neg_lo:[0,0,1] neg_hi:[0,0,1]
	s_nop 0
	v_cvt_pk_bf16_f32 v60, v48, v49
	v_lshlrev_b32_e32 v48, 16, v61
	v_and_b32_e32 v49, 0xffff0000, v61
	v_pk_fma_f32 v[46:47], v[44:45], v[46:47], v[48:49] neg_lo:[0,0,1] neg_hi:[0,0,1]
	v_mov_b32_e32 v49, 0
	v_cvt_pk_bf16_f32 v61, v46, v47
	v_lshl_add_u64 v[46:47], v[40:41], 0, v[160:161]
	global_load_dwordx4 v[76:79], v[46:47], off offset:64
	v_mov_b32_e32 v48, v49
	v_mov_b32_e32 v51, v49
	v_mov_b32_e32 v50, v49
	v_mov_b32_e32 v53, v49
	v_mov_b32_e32 v52, v49
	v_mov_b32_e32 v47, v49
	v_mov_b32_e32 v46, v49
	s_waitcnt vmcnt(1)
	v_mfma_f32_32x32x16_bf16 v[16:31], v[58:61], v[72:75], v[16:31]
	s_waitcnt vmcnt(0)
	v_mfma_f32_32x32x16_bf16 v[0:15], v[58:61], v[76:79], v[0:15]
	s_and_saveexec_b64 s[0:1], s[38:39]
	s_cbranch_execz .LBB0_155
	v_sub_u32_e32 v46, v107, v106
	v_readlane_b32 s2, v246, 36
	s_mov_b64 s[8:9], 0
	v_mov_b32_e32 v59, v105
	v_add_u32_e32 v58, s2, v46
	v_mov_b32_e32 v46, 0
	v_mov_b32_e32 v47, v46
	v_mov_b32_e32 v52, v46
	v_mov_b32_e32 v53, v46
	v_mov_b32_e32 v50, v46
	v_mov_b32_e32 v51, v46
	v_mov_b32_e32 v48, v46
	v_mov_b32_e32 v49, v46
	ds_read_b128 v[60:63], v58
	v_add_u32_e32 v58, 0x90, v58
; DI unsigned pk2(float lo, float hi) { f32x2 v = {lo, hi}; bfv2 b = __builtin_convertvector(v, bfv2); return __builtin_bit_cast(unsigned, b); }
; DI f32x16 mfma32(bf16x8 a, bf16x8 b, f32x16 c) { return __builtin_amdgcn_mfma_f32_32x32x16_bf16(a, b, c, 0, 0, 0); }
; DI void unpack8(u32x4 v, float* x) { x[0] = bflo(v.x); x[1] = bfhi(v.x); x[2] = bflo(v.y); x[3] = bfhi(v.y); x[4] = bflo(v.z); x[5] = bfhi(v.z); x[6] = bflo(v.w); x[7] = bfhi(v.w); }
; DI void pool_task(const Params& p, int layer, int tile, unsigned char* lds) {
;     ...
;   for (int mt = 0; mt < 2; ++mt) {
;     const int tl = 32 * mt + r, pos = t0 + tl - s0;
;     const int lo = max(pos - half, 0), hi = min(pos + half, S);
;     const float inv = 1.f / (float)(hi - lo);
; #pragma unroll
;     for (int ks = 0; ks < 4; ++ks) {
;       float sum[8];
; #pragma unroll
;       for (int e = 0; e < 8; ++e) sum[e] = 0.f;
;       for (int w = 0; w < 2 * half; ++w) {
;         float x[8]; unpack8(*(const u32x4*)(xs + (tl + 8 - half + w) * 72 + 16 * ks + 8 * hh), x);
; #pragma unroll
;         for (int e = 0; e < 8; ++e) sum[e] += x[e];
;       }
;       float x0[8]; unpack8(*(const u32x4*)(xs + (tl + 8) * 72 + 16 * ks + 8 * hh), x0);
;       const u32x4 w4 = {pk2(sum[0] * inv - x0[0], sum[1] * inv - x0[1]), pk2(sum[2] * inv - x0[2], sum[3] * inv - x0[3]), pk2(sum[4] * inv - x0[4], sum[5] * inv - x0[5]), pk2(sum[6] * inv - x0[6], sum[7] * inv - x0[7])};
;       const bf16x8 a = __builtin_bit_cast(bf16x8, w4);
; #pragma unroll
;       for (int nt = 0; nt < 2; ++nt) { const bf16x8 b = *(const bf16x8*)(WT + (32 * nt + r) * 64 + 16 * ks + 8 * hh); acc[mt][nt] = mfma32(a, b, acc[mt][nt]); }
;     }
.LBB0_153:
	ds_read_b128 v[236:239], v58
	v_add_u32_e32 v59, -2, v59
	v_cmp_eq_u32_e32 vcc, 0, v59
	v_add_u32_e32 v58, 0x90, v58
	s_or_b64 s[8:9], vcc, s[8:9]
	s_waitcnt lgkmcnt(1)
	v_lshlrev_b32_e32 v80, 16, v60
	v_and_b32_e32 v81, 0xffff0000, v60
	v_lshlrev_b32_e32 v60, 16, v61
	v_and_b32_e32 v61, 0xffff0000, v61
	v_pk_add_f32 v[50:51], v[50:51], v[60:61]
	v_lshlrev_b32_e32 v60, 16, v62
	v_and_b32_e32 v61, 0xffff0000, v62
	v_pk_add_f32 v[48:49], v[48:49], v[60:61]
	v_lshlrev_b32_e32 v60, 16, v63
	v_and_b32_e32 v61, 0xffff0000, v63
	v_pk_add_f32 v[52:53], v[52:53], v[80:81]
	v_pk_add_f32 v[46:47], v[46:47], v[60:61]
	ds_read_b128 v[60:63], v58
	v_add_u32_e32 v58, 0x90, v58
	s_waitcnt lgkmcnt(1)
	v_lshlrev_b32_e32 v80, 16, v236
	v_and_b32_e32 v81, 0xffff0000, v236
	v_lshlrev_b32_e32 v236, 16, v237
	v_and_b32_e32 v237, 0xffff0000, v237
	v_pk_add_f32 v[50:51], v[50:51], v[236:237]
	v_lshlrev_b32_e32 v236, 16, v238
	v_and_b32_e32 v237, 0xffff0000, v238
	v_pk_add_f32 v[48:49], v[48:49], v[236:237]
	v_lshlrev_b32_e32 v236, 16, v239
	v_and_b32_e32 v237, 0xffff0000, v239
	v_pk_add_f32 v[52:53], v[52:53], v[80:81]
	v_pk_add_f32 v[46:47], v[46:47], v[236:237]
	s_andn2_b64 exec, exec, s[8:9]
	s_cbranch_execnz .LBB0_153
	s_or_b64 exec, exec, s[8:9]
	s_waitcnt lgkmcnt(0)
.LBB0_155:
	s_or_b64 exec, exec, s[0:1]
	v_lshl_add_u64 v[40:41], v[40:41], 0, v[160:161]
	global_load_dwordx4 v[80:83], v[42:43], off offset:96
	global_load_dwordx4 v[84:87], v[40:41], off offset:96
	ds_read_b128 v[58:61], v57 offset:1248
	v_mov_b32_e32 v43, 0
	v_mov_b32_e32 v42, v43
	v_mov_b32_e32 v41, v43
	v_mov_b32_e32 v40, v43
	s_waitcnt lgkmcnt(0)
	v_lshlrev_b32_e32 v62, 16, v58
	v_and_b32_e32 v63, 0xffff0000, v58
	v_pk_fma_f32 v[52:53], v[44:45], v[52:53], v[62:63] neg_lo:[0,0,1] neg_hi:[0,0,1]
	s_nop 0
	v_cvt_pk_bf16_f32 v58, v52, v53
	v_lshlrev_b32_e32 v52, 16, v59
	v_and_b32_e32 v53, 0xffff0000, v59
	v_pk_fma_f32 v[50:51], v[44:45], v[50:51], v[52:53] neg_lo:[0,0,1] neg_hi:[0,0,1]
	s_nop 0
	v_cvt_pk_bf16_f32 v59, v50, v51
	v_lshlrev_b32_e32 v50, 16, v60
	v_and_b32_e32 v51, 0xffff0000, v60
	v_pk_fma_f32 v[48:49], v[44:45], v[48:49], v[50:51] neg_lo:[0,0,1] neg_hi:[0,0,1]
	s_nop 0
	v_cvt_pk_bf16_f32 v60, v48, v49
	v_lshlrev_b32_e32 v48, 16, v61
	v_and_b32_e32 v49, 0xffff0000, v61
	v_pk_fma_f32 v[44:45], v[44:45], v[46:47], v[48:49] neg_lo:[0,0,1] neg_hi:[0,0,1]
	v_mov_b32_e32 v47, v43
	v_cvt_pk_bf16_f32 v61, v44, v45
	v_mov_b32_e32 v45, v43
	v_mov_b32_e32 v44, v43
	v_mov_b32_e32 v46, v43
	s_waitcnt vmcnt(1)
	v_mfma_f32_32x32x16_bf16 v[16:31], v[58:61], v[80:83], v[16:31]
	s_waitcnt vmcnt(0)
	v_mfma_f32_32x32x16_bf16 v[0:15], v[58:61], v[84:87], v[0:15]
	s_and_saveexec_b64 s[0:1], s[38:39]
	s_cbranch_execz .LBB0_159
	v_sub_u32_e32 v40, v107, v106
	v_readlane_b32 s2, v246, 37
	s_mov_b64 s[8:9], 0
	v_mov_b32_e32 v49, v105
	v_add_u32_e32 v48, s2, v40
	v_mov_b32_e32 v40, 0
	v_mov_b32_e32 v41, v40
	v_mov_b32_e32 v46, v40
	v_mov_b32_e32 v47, v40
	v_mov_b32_e32 v44, v40
	v_mov_b32_e32 v45, v40
	v_mov_b32_e32 v42, v40
	v_mov_b32_e32 v43, v40
	ds_read_b128 v[50:53], v48
	v_add_u32_e32 v48, 0x90, v48
.LBB0_157:
	ds_read_b128 v[236:239], v48
	v_add_u32_e32 v49, -2, v49
	v_cmp_eq_u32_e32 vcc, 0, v49
	v_add_u32_e32 v48, 0x90, v48
	s_or_b64 s[8:9], vcc, s[8:9]
	s_waitcnt lgkmcnt(1)
	v_lshlrev_b32_e32 v58, 16, v50
	v_and_b32_e32 v59, 0xffff0000, v50
	v_lshlrev_b32_e32 v50, 16, v51
	v_and_b32_e32 v51, 0xffff0000, v51
	v_pk_add_f32 v[44:45], v[44:45], v[50:51]
	v_lshlrev_b32_e32 v50, 16, v52
	v_and_b32_e32 v51, 0xffff0000, v52
	v_pk_add_f32 v[42:43], v[42:43], v[50:51]
	v_lshlrev_b32_e32 v50, 16, v53
	v_and_b32_e32 v51, 0xffff0000, v53
	v_pk_add_f32 v[46:47], v[46:47], v[58:59]
	v_pk_add_f32 v[40:41], v[40:41], v[50:51]
	ds_read_b128 v[50:53], v48
	v_add_u32_e32 v48, 0x90, v48
	s_waitcnt lgkmcnt(1)
	v_lshlrev_b32_e32 v58, 16, v236
	v_and_b32_e32 v59, 0xffff0000, v236
	v_lshlrev_b32_e32 v236, 16, v237
	v_and_b32_e32 v237, 0xffff0000, v237
	v_pk_add_f32 v[44:45], v[44:45], v[236:237]
	v_lshlrev_b32_e32 v236, 16, v238
	v_and_b32_e32 v237, 0xffff0000, v238
	v_pk_add_f32 v[42:43], v[42:43], v[236:237]
	v_lshlrev_b32_e32 v236, 16, v239
	v_and_b32_e32 v237, 0xffff0000, v239
	v_pk_add_f32 v[46:47], v[46:47], v[58:59]
	v_pk_add_f32 v[40:41], v[40:41], v[236:237]
	s_andn2_b64 exec, exec, s[8:9]
	s_cbranch_execnz .LBB0_157
	s_or_b64 exec, exec, s[8:9]
	s_waitcnt lgkmcnt(0)
.LBB0_159:
	s_or_b64 exec, exec, s[0:1]
	v_or_b32_e32 v48, 32, v104
	v_or_b32_e32 v49, s34, v48
	v_subrev_u32_e32 v49, s35, v49
	v_sub_u32_e32 v50, v49, v55
	v_add_u32_e32 v49, v49, v55
	v_max_i32_e32 v50, 0, v50
	v_min_i32_e32 v49, s21, v49
	v_sub_u32_e32 v49, v49, v50
	v_cvt_f32_i32_e32 v52, v49
	v_mul_u32_u24_e32 v48, 0x90, v48
	v_div_scale_f32 v53, s[0:1], v52, v52, 1.0
	v_rcp_f32_e32 v55, v53
	v_div_scale_f32 v57, vcc, 1.0, v52, 1.0
	v_fma_f32 v49, -v53, v55, 1.0
	v_fmac_f32_e32 v55, v49, v55
	v_mul_f32_e32 v58, v57, v55
	v_fma_f32 v49, -v53, v58, v57
	v_fmac_f32_e32 v58, v49, v55
	v_lshlrev_b32_e32 v49, 1, v56
	v_add3_u32 v108, v54, v48, v49
	ds_read_b128 v[48:51], v108 offset:1152
	v_fma_f32 v53, -v53, v58, v57
	v_div_fmas_f32 v53, v53, v55, v58
	v_div_fixup_f32 v90, v53, v52, 1.0
	s_waitcnt lgkmcnt(0)
	v_lshlrev_b32_e32 v52, 16, v48
	v_and_b32_e32 v53, 0xffff0000, v48
	v_pk_fma_f32 v[46:47], v[90:91], v[46:47], v[52:53] op_sel_hi:[0,1,1] neg_lo:[0,0,1] neg_hi:[0,0,1]
	v_cvt_pk_bf16_f32 v92, v46, v47
	v_lshlrev_b32_e32 v46, 16, v49
	v_and_b32_e32 v47, 0xffff0000, v49
	v_pk_fma_f32 v[44:45], v[90:91], v[44:45], v[46:47] op_sel_hi:[0,1,1] neg_lo:[0,0,1] neg_hi:[0,0,1]
	v_cvt_pk_bf16_f32 v93, v44, v45
	v_lshlrev_b32_e32 v44, 16, v50
	v_and_b32_e32 v45, 0xffff0000, v50
	v_pk_fma_f32 v[42:43], v[90:91], v[42:43], v[44:45] op_sel_hi:[0,1,1] neg_lo:[0,0,1] neg_hi:[0,0,1]
	v_cvt_pk_bf16_f32 v94, v42, v43
	v_lshlrev_b32_e32 v42, 16, v51
	v_and_b32_e32 v43, 0xffff0000, v51
	v_pk_fma_f32 v[40:41], v[90:91], v[40:41], v[42:43] op_sel_hi:[0,1,1] neg_lo:[0,0,1] neg_hi:[0,0,1]
	v_cvt_pk_bf16_f32 v95, v40, v41
	s_nop 1
	v_mfma_f32_32x32x16_bf16 v[48:63], v[92:95], v[32:35], 0
	v_mfma_f32_32x32x16_bf16 v[32:47], v[92:95], v[36:39], 0
	v_mov_b32_e32 v95, 0
	v_mov_b32_e32 v94, v95
	v_mov_b32_e32 v97, v95
	v_mov_b32_e32 v96, v95
	v_mov_b32_e32 v99, v95
	v_mov_b32_e32 v98, v95
	v_mov_b32_e32 v93, v95
	v_mov_b32_e32 v92, v95
	s_and_saveexec_b64 s[0:1], s[38:39]
	s_cbranch_execz .LBB0_163
	v_sub_u32_e32 v91, v107, v106
	v_readlane_b32 s2, v246, 38
	v_mov_b32_e32 v92, 0
	s_mov_b64 s[8:9], 0
	v_add_u32_e32 v91, s2, v91
	v_mov_b32_e32 v109, v105
	v_mov_b32_e32 v93, v92
	v_mov_b32_e32 v98, v92
	v_mov_b32_e32 v99, v92
	v_mov_b32_e32 v96, v92
	v_mov_b32_e32 v97, v92
	v_mov_b32_e32 v94, v92
	v_mov_b32_e32 v95, v92
	ds_read_b128 v[110:113], v91
	v_add_u32_e32 v91, 0x90, v91
; DI unsigned pk2(float lo, float hi) { f32x2 v = {lo, hi}; bfv2 b = __builtin_convertvector(v, bfv2); return __builtin_bit_cast(unsigned, b); }
; DI f32x16 mfma32(bf16x8 a, bf16x8 b, f32x16 c) { return __builtin_amdgcn_mfma_f32_32x32x16_bf16(a, b, c, 0, 0, 0); }
; DI void unpack8(u32x4 v, float* x) { x[0] = bflo(v.x); x[1] = bfhi(v.x); x[2] = bflo(v.y); x[3] = bfhi(v.y); x[4] = bflo(v.z); x[5] = bfhi(v.z); x[6] = bflo(v.w); x[7] = bfhi(v.w); }
; DI void pool_task(const Params& p, int layer, int tile, unsigned char* lds) {
;     ...
;     for (int ks = 0; ks < 4; ++ks) {
;       float sum[8];
; #pragma unroll
;       for (int e = 0; e < 8; ++e) sum[e] = 0.f;
;       for (int w = 0; w < 2 * half; ++w) {
;         float x[8]; unpack8(*(const u32x4*)(xs + (tl + 8 - half + w) * 72 + 16 * ks + 8 * hh), x);
; #pragma unroll
;         for (int e = 0; e < 8; ++e) sum[e] += x[e];
;       }
;       float x0[8]; unpack8(*(const u32x4*)(xs + (tl + 8) * 72 + 16 * ks + 8 * hh), x0);
;       const u32x4 w4 = {pk2(sum[0] * inv - x0[0], sum[1] * inv - x0[1]), pk2(sum[2] * inv - x0[2], sum[3] * inv - x0[3]), pk2(sum[4] * inv - x0[4], sum[5] * inv - x0[5]), pk2(sum[6] * inv - x0[6], sum[7] * inv - x0[7])};
;       const bf16x8 a = __builtin_bit_cast(bf16x8, w4);
; #pragma unroll
;       for (int nt = 0; nt < 2; ++nt) { const bf16x8 b = *(const bf16x8*)(WT + (32 * nt + r) * 64 + 16 * ks + 8 * hh); acc[mt][nt] = mfma32(a, b, acc[mt][nt]); }
;     }
.LBB0_161:
	ds_read_b128 v[236:239], v91
	v_add_u32_e32 v109, -2, v109
	v_cmp_eq_u32_e32 vcc, 0, v109
	v_add_u32_e32 v91, 0x90, v91
	s_or_b64 s[8:9], vcc, s[8:9]
	s_waitcnt lgkmcnt(1)
	v_lshlrev_b32_e32 v114, 16, v110
	v_and_b32_e32 v115, 0xffff0000, v110
	v_lshlrev_b32_e32 v110, 16, v111
	v_and_b32_e32 v111, 0xffff0000, v111
	v_pk_add_f32 v[96:97], v[96:97], v[110:111]
	v_lshlrev_b32_e32 v110, 16, v112
	v_and_b32_e32 v111, 0xffff0000, v112
	v_pk_add_f32 v[94:95], v[94:95], v[110:111]
	v_lshlrev_b32_e32 v110, 16, v113
	v_and_b32_e32 v111, 0xffff0000, v113
	v_pk_add_f32 v[98:99], v[98:99], v[114:115]
	v_pk_add_f32 v[92:93], v[92:93], v[110:111]
	ds_read_b128 v[110:113], v91
	v_add_u32_e32 v91, 0x90, v91
	s_waitcnt lgkmcnt(1)
	v_lshlrev_b32_e32 v114, 16, v236
	v_and_b32_e32 v115, 0xffff0000, v236
	v_lshlrev_b32_e32 v236, 16, v237
	v_and_b32_e32 v237, 0xffff0000, v237
	v_pk_add_f32 v[96:97], v[96:97], v[236:237]
	v_lshlrev_b32_e32 v236, 16, v238
	v_and_b32_e32 v237, 0xffff0000, v238
	v_pk_add_f32 v[94:95], v[94:95], v[236:237]
	v_lshlrev_b32_e32 v236, 16, v239
	v_and_b32_e32 v237, 0xffff0000, v239
	v_pk_add_f32 v[98:99], v[98:99], v[114:115]
	v_pk_add_f32 v[92:93], v[92:93], v[236:237]
	s_andn2_b64 exec, exec, s[8:9]
	s_cbranch_execnz .LBB0_161
	s_or_b64 exec, exec, s[8:9]
	s_waitcnt lgkmcnt(0)
.LBB0_163:
	s_or_b64 exec, exec, s[0:1]
	ds_read_b128 v[110:113], v108 offset:1184
	v_mov_b32_e32 v91, v90
	s_waitcnt lgkmcnt(0)
	v_lshlrev_b32_e32 v114, 16, v110
	v_and_b32_e32 v115, 0xffff0000, v110
	v_pk_fma_f32 v[98:99], v[90:91], v[98:99], v[114:115] neg_lo:[0,0,1] neg_hi:[0,0,1]
	s_nop 0
	v_cvt_pk_bf16_f32 v110, v98, v99
	v_lshlrev_b32_e32 v98, 16, v111
	v_and_b32_e32 v99, 0xffff0000, v111
	v_pk_fma_f32 v[96:97], v[90:91], v[96:97], v[98:99] neg_lo:[0,0,1] neg_hi:[0,0,1]
	s_nop 0
	v_cvt_pk_bf16_f32 v111, v96, v97
	v_lshlrev_b32_e32 v96, 16, v112
	v_and_b32_e32 v97, 0xffff0000, v112
	v_pk_fma_f32 v[94:95], v[90:91], v[94:95], v[96:97] neg_lo:[0,0,1] neg_hi:[0,0,1]
	s_nop 0
	v_cvt_pk_bf16_f32 v112, v94, v95
	v_lshlrev_b32_e32 v94, 16, v113
	v_and_b32_e32 v95, 0xffff0000, v113
	v_pk_fma_f32 v[92:93], v[90:91], v[92:93], v[94:95] neg_lo:[0,0,1] neg_hi:[0,0,1]
	s_nop 0
	v_cvt_pk_bf16_f32 v113, v92, v93
	s_nop 1
	v_mfma_f32_32x32x16_bf16 v[48:63], v[110:113], v[64:67], v[48:63]
	v_mov_b32_e32 v67, 0
	v_mov_b32_e32 v66, v67
	v_mov_b32_e32 v65, v67
	v_mov_b32_e32 v64, v67
	v_mfma_f32_32x32x16_bf16 v[32:47], v[110:113], v[68:71], v[32:47]
	v_mov_b32_e32 v69, v67
	v_mov_b32_e32 v68, v67
	v_mov_b32_e32 v71, v67
	v_mov_b32_e32 v70, v67
	s_and_saveexec_b64 s[0:1], s[38:39]
	s_cbranch_execz .LBB0_167
	v_sub_u32_e32 v64, v107, v106
	v_readlane_b32 s2, v246, 39
	s_mov_b64 s[8:9], 0
	v_mov_b32_e32 v93, v105
	v_add_u32_e32 v92, s2, v64
	v_mov_b32_e32 v64, 0
	v_mov_b32_e32 v65, v64
	v_mov_b32_e32 v70, v64
	v_mov_b32_e32 v71, v64
	v_mov_b32_e32 v68, v64
	v_mov_b32_e32 v69, v64
	v_mov_b32_e32 v66, v64
	v_mov_b32_e32 v67, v64
	ds_read_b128 v[94:97], v92
	v_add_u32_e32 v92, 0x90, v92
; DI unsigned pk2(float lo, float hi) { f32x2 v = {lo, hi}; bfv2 b = __builtin_convertvector(v, bfv2); return __builtin_bit_cast(unsigned, b); }
; DI f32x16 mfma32(bf16x8 a, bf16x8 b, f32x16 c) { return __builtin_amdgcn_mfma_f32_32x32x16_bf16(a, b, c, 0, 0, 0); }
; DI void unpack8(u32x4 v, float* x) { x[0] = bflo(v.x); x[1] = bfhi(v.x); x[2] = bflo(v.y); x[3] = bfhi(v.y); x[4] = bflo(v.z); x[5] = bfhi(v.z); x[6] = bflo(v.w); x[7] = bfhi(v.w); }
; DI void pool_task(const Params& p, int layer, int tile, unsigned char* lds) {
;     ...
;     for (int ks = 0; ks < 4; ++ks) {
;       float sum[8];
; #pragma unroll
;       for (int e = 0; e < 8; ++e) sum[e] = 0.f;
;       for (int w = 0; w < 2 * half; ++w) {
;         float x[8]; unpack8(*(const u32x4*)(xs + (tl + 8 - half + w) * 72 + 16 * ks + 8 * hh), x);
; #pragma unroll
;         for (int e = 0; e < 8; ++e) sum[e] += x[e];
;       }
;       float x0[8]; unpack8(*(const u32x4*)(xs + (tl + 8) * 72 + 16 * ks + 8 * hh), x0);
;       const u32x4 w4 = {pk2(sum[0] * inv - x0[0], sum[1] * inv - x0[1]), pk2(sum[2] * inv - x0[2], sum[3] * inv - x0[3]), pk2(sum[4] * inv - x0[4], sum[5] * inv - x0[5]), pk2(sum[6] * inv - x0[6], sum[7] * inv - x0[7])};
;       const bf16x8 a = __builtin_bit_cast(bf16x8, w4);
; #pragma unroll
;       for (int nt = 0; nt < 2; ++nt) { const bf16x8 b = *(const bf16x8*)(WT + (32 * nt + r) * 64 + 16 * ks + 8 * hh); acc[mt][nt] = mfma32(a, b, acc[mt][nt]); }
;     }
.LBB0_165:
	ds_read_b128 v[236:239], v92
	v_add_u32_e32 v93, -2, v93
	v_cmp_eq_u32_e32 vcc, 0, v93
	v_add_u32_e32 v92, 0x90, v92
	s_or_b64 s[8:9], vcc, s[8:9]
	s_waitcnt lgkmcnt(1)
	v_lshlrev_b32_e32 v98, 16, v94
	v_and_b32_e32 v99, 0xffff0000, v94
	v_lshlrev_b32_e32 v94, 16, v95
	v_and_b32_e32 v95, 0xffff0000, v95
	v_pk_add_f32 v[68:69], v[68:69], v[94:95]
	v_lshlrev_b32_e32 v94, 16, v96
	v_and_b32_e32 v95, 0xffff0000, v96
	v_pk_add_f32 v[66:67], v[66:67], v[94:95]
	v_lshlrev_b32_e32 v94, 16, v97
	v_and_b32_e32 v95, 0xffff0000, v97
	v_pk_add_f32 v[70:71], v[70:71], v[98:99]
	v_pk_add_f32 v[64:65], v[64:65], v[94:95]
	ds_read_b128 v[94:97], v92
	v_add_u32_e32 v92, 0x90, v92
	s_waitcnt lgkmcnt(1)
	v_lshlrev_b32_e32 v98, 16, v236
	v_and_b32_e32 v99, 0xffff0000, v236
	v_lshlrev_b32_e32 v236, 16, v237
	v_and_b32_e32 v237, 0xffff0000, v237
	v_pk_add_f32 v[68:69], v[68:69], v[236:237]
	v_lshlrev_b32_e32 v236, 16, v238
	v_and_b32_e32 v237, 0xffff0000, v238
	v_pk_add_f32 v[66:67], v[66:67], v[236:237]
	v_lshlrev_b32_e32 v236, 16, v239
	v_and_b32_e32 v237, 0xffff0000, v239
	v_pk_add_f32 v[70:71], v[70:71], v[98:99]
	v_pk_add_f32 v[64:65], v[64:65], v[236:237]
	s_andn2_b64 exec, exec, s[8:9]
	s_cbranch_execnz .LBB0_165
	s_or_b64 exec, exec, s[8:9]
	s_waitcnt lgkmcnt(0)
.LBB0_167:
	s_or_b64 exec, exec, s[0:1]
	ds_read_b128 v[92:95], v108 offset:1216
	s_waitcnt lgkmcnt(0)
	v_lshlrev_b32_e32 v96, 16, v92
	v_and_b32_e32 v97, 0xffff0000, v92
	v_pk_fma_f32 v[70:71], v[90:91], v[70:71], v[96:97] neg_lo:[0,0,1] neg_hi:[0,0,1]
	s_nop 0
	v_cvt_pk_bf16_f32 v92, v70, v71
	v_lshlrev_b32_e32 v70, 16, v93
	v_and_b32_e32 v71, 0xffff0000, v93
	v_pk_fma_f32 v[68:69], v[90:91], v[68:69], v[70:71] neg_lo:[0,0,1] neg_hi:[0,0,1]
	s_nop 0
	v_cvt_pk_bf16_f32 v93, v68, v69
	v_lshlrev_b32_e32 v68, 16, v94
	v_and_b32_e32 v69, 0xffff0000, v94
	v_pk_fma_f32 v[66:67], v[90:91], v[66:67], v[68:69] neg_lo:[0,0,1] neg_hi:[0,0,1]
	s_nop 0
	v_cvt_pk_bf16_f32 v94, v66, v67
	v_lshlrev_b32_e32 v66, 16, v95
	v_and_b32_e32 v67, 0xffff0000, v95
	v_pk_fma_f32 v[64:65], v[90:91], v[64:65], v[66:67] neg_lo:[0,0,1] neg_hi:[0,0,1]
	v_mov_b32_e32 v67, 0
	v_cvt_pk_bf16_f32 v95, v64, v65
	v_mov_b32_e32 v66, v67
	v_mov_b32_e32 v69, v67
	v_mfma_f32_32x32x16_bf16 v[48:63], v[92:95], v[72:75], v[48:63]
	v_mov_b32_e32 v68, v67
	v_mov_b32_e32 v71, v67
	v_mov_b32_e32 v70, v67
	v_mov_b32_e32 v65, v67
	v_mov_b32_e32 v64, v67
	v_mfma_f32_32x32x16_bf16 v[32:47], v[92:95], v[76:79], v[32:47]
	s_and_saveexec_b64 s[0:1], s[38:39]
	s_cbranch_execz .LBB0_171
	v_sub_u32_e32 v64, v107, v106
	v_readlane_b32 s2, v246, 40
	s_mov_b64 s[8:9], 0
	s_nop 0
	v_add_u32_e32 v72, s2, v64
	v_mov_b32_e32 v64, 0
	v_mov_b32_e32 v65, v64
	v_mov_b32_e32 v70, v64
	v_mov_b32_e32 v71, v64
	v_mov_b32_e32 v68, v64
	v_mov_b32_e32 v69, v64
	v_mov_b32_e32 v66, v64
	v_mov_b32_e32 v67, v64
	ds_read_b128 v[74:77], v72
	v_add_u32_e32 v72, 0x90, v72
.LBB0_169:
	ds_read_b128 v[236:239], v72
	v_add_u32_e32 v105, -2, v105
	v_cmp_eq_u32_e32 vcc, 0, v105
	v_add_u32_e32 v72, 0x90, v72
	s_or_b64 s[8:9], vcc, s[8:9]
	s_waitcnt lgkmcnt(1)
	v_lshlrev_b32_e32 v78, 16, v74
	v_and_b32_e32 v79, 0xffff0000, v74
	v_lshlrev_b32_e32 v74, 16, v75
	v_and_b32_e32 v75, 0xffff0000, v75
	v_pk_add_f32 v[68:69], v[68:69], v[74:75]
	v_lshlrev_b32_e32 v74, 16, v76
	v_and_b32_e32 v75, 0xffff0000, v76
	v_pk_add_f32 v[66:67], v[66:67], v[74:75]
	v_lshlrev_b32_e32 v74, 16, v77
	v_and_b32_e32 v75, 0xffff0000, v77
	v_pk_add_f32 v[70:71], v[70:71], v[78:79]
	v_pk_add_f32 v[64:65], v[64:65], v[74:75]
	ds_read_b128 v[74:77], v72
	v_add_u32_e32 v72, 0x90, v72
	s_waitcnt lgkmcnt(1)
	v_lshlrev_b32_e32 v78, 16, v236
	v_and_b32_e32 v79, 0xffff0000, v236
	v_lshlrev_b32_e32 v236, 16, v237
	v_and_b32_e32 v237, 0xffff0000, v237
	v_pk_add_f32 v[68:69], v[68:69], v[236:237]
	v_lshlrev_b32_e32 v236, 16, v238
	v_and_b32_e32 v237, 0xffff0000, v238
	v_pk_add_f32 v[66:67], v[66:67], v[236:237]
	v_lshlrev_b32_e32 v236, 16, v239
	v_and_b32_e32 v237, 0xffff0000, v239
	v_pk_add_f32 v[70:71], v[70:71], v[78:79]
	v_pk_add_f32 v[64:65], v[64:65], v[236:237]
	s_andn2_b64 exec, exec, s[8:9]
	s_cbranch_execnz .LBB0_169
	s_or_b64 exec, exec, s[8:9]
	s_waitcnt lgkmcnt(0)
